# hg_out V^T element loads issued before the cumulative-sum barrier instead of after it
# baseline (speedup 1.0000x reference)
; __device__ __forceinline__ float sigmoidf_(float x) { return 1.0f / (1.0f + __expf(-x)); }
; __device__ __forceinline__ void hg_bcum(const Params& p, int l, const u16* Uhg, int t0, int h, float* bc, float* lbs,
;                                         float* tots) {
;     ...
;   for (int k = 0; k < 4; ++k) {
;     const int s = (tid >> 4) + 16 * k, d0 = (tid & 15) * 8;
;     float z[8];
;     unpack8(*(const uint4*)(Uhg + (size_t)(t0 + s) * 2048 + 512 + h * 128 + d0), z);
;     float lf[8];
; #pragma unroll
;     for (int j = 0; j < 8; ++j) {
;       const float lbv = lbs[d0 + j];
;       const float f = lbv + (1.0f - lbv) * sigmoidf_(z[j]);
;       lf[j] = __logf(fmaxf(f, 1e-30f));
;     }
;     *(float4*)(bc + s * BCS + d0) = make_float4(lf[0], lf[1], lf[2], lf[3]);
;     *(float4*)(bc + s * BCS + d0 + 4) = make_float4(lf[4], lf[5], lf[6], lf[7]);
.LBB0_39:
	s_or_b64 exec, exec, s[0:1]
	s_and_b32 s12, s86, 0x7f
	s_lshl_b32 s0, s86, 4
	s_and_b32 s0, s0, 0xffffe000
	s_lshl_b32 s1, s12, 6
	s_or_b32 s13, s0, s1
	v_lshrrev_b32_e32 v59, 4, v34
	v_or_b32_e32 v46, s13, v59
	v_lshlrev_b32_e32 v34, 3, v50
	v_ashrrev_i32_e32 v47, 31, v46
	v_readlane_b32 s22, v252, 46
	v_and_b32_e32 v36, 0x78, v34
	v_lshlrev_b64 v[34:35], 12, v[46:47]
	v_readlane_b32 s23, v252, 47
	s_lshl_b32 s58, s20, 8
	v_lshlrev_b32_e32 v48, 1, v36
	v_lshl_add_u64 v[34:35], s[22:23], 0, v[34:35]
	v_lshl_add_u64 v[34:35], v[34:35], 0, s[58:59]
	v_mov_b32_e32 v49, v1
	v_lshl_add_u64 v[34:35], v[34:35], 0, v[48:49]
	s_waitcnt lgkmcnt(0)
	s_barrier
	v_lshl_add_u32 v64, v36, 2, s69
	s_mov_b32 s98, 0x10000
	s_mov_b32 s99, 0
	v_lshl_add_u64 v[110:111], v[34:35], 0, s[98:99]
	global_load_dwordx4 v[34:37], v[34:35], off offset:1024
	global_load_dwordx4 v[98:101], v[110:111], off offset:1024
	v_lshl_add_u64 v[110:111], v[110:111], 0, s[98:99]
	global_load_dwordx4 v[102:105], v[110:111], off offset:1024
	v_lshl_add_u64 v[110:111], v[110:111], 0, s[98:99]
	global_load_dwordx4 v[106:109], v[110:111], off offset:1024
	s_waitcnt vmcnt(3)
	v_lshlrev_b32_e32 v42, 16, v34
	v_mul_f32_e32 v42, 0xbfb8aa3b, v42
	v_exp_f32_e32 v42, v42
	v_and_b32_e32 v43, 0xffff0000, v34
	v_lshlrev_b32_e32 v44, 16, v35
	v_and_b32_e32 v45, 0xffff0000, v35
	v_add_f32_e32 v42, 1.0, v42
	v_div_scale_f32 v52, s[0:1], v42, v42, 1.0
	v_rcp_f32_e32 v53, v52
	v_lshlrev_b32_e32 v47, 16, v36
	v_and_b32_e32 v51, 0xffff0000, v36
	v_lshlrev_b32_e32 v62, 16, v37
	v_fma_f32 v54, -v52, v53, 1.0
	v_fmac_f32_e32 v53, v54, v53
	v_div_scale_f32 v54, vcc, 1.0, v42, 1.0
	v_mul_f32_e32 v55, v54, v53
	v_and_b32_e32 v63, 0xffff0000, v37
	ds_read_b128 v[38:41], v64 offset:33792
	ds_read_b128 v[34:37], v64 offset:33808
	v_fma_f32 v56, -v52, v55, v54
	v_fmac_f32_e32 v55, v56, v53
	v_fma_f32 v52, -v52, v55, v54
	v_div_fmas_f32 v52, v52, v53, v55
	s_waitcnt lgkmcnt(1)
	v_sub_f32_e32 v58, 1.0, v38
	v_div_fixup_f32 v42, v52, v42, 1.0
	v_fma_f32 v42, v58, v42, v38
	v_max_f32_e32 v42, 0xda24260, v42
	v_cmp_gt_f32_e32 vcc, s56, v42
	v_mul_f32_e32 v43, 0xbfb8aa3b, v43
	v_exp_f32_e32 v43, v43
	v_cndmask_b32_e64 v52, 0, 32, vcc
	v_ldexp_f32 v42, v42, v52
	v_log_f32_e32 v42, v42
	v_add_f32_e32 v43, 1.0, v43
	v_sub_f32_e32 v57, 1.0, v39
	v_mul_f32_e32 v44, 0xbfb8aa3b, v44
	v_mul_f32_e32 v52, 0x3f317217, v42
	v_fma_f32 v52, v42, s57, -v52
	v_fmac_f32_e32 v52, 0x3377d1cf, v42
	v_fmac_f32_e32 v52, 0x3f317217, v42
	v_cmp_lt_f32_e64 s[0:1], |v42|, s8
	v_exp_f32_e32 v44, v44
	v_mul_f32_e32 v45, 0xbfb8aa3b, v45
	v_cndmask_b32_e64 v42, v42, v52, s[0:1]
	v_cndmask_b32_e32 v52, 0, v201, vcc
	v_sub_f32_e32 v42, v42, v52
	v_div_scale_f32 v52, s[0:1], v43, v43, 1.0
	v_rcp_f32_e32 v53, v52
	v_add_f32_e32 v44, 1.0, v44
	v_exp_f32_e32 v45, v45
	v_mul_f32_e32 v47, 0xbfb8aa3b, v47
	v_fma_f32 v54, -v52, v53, 1.0
	v_fmac_f32_e32 v53, v54, v53
	v_div_scale_f32 v54, vcc, 1.0, v43, 1.0
	v_mul_f32_e32 v55, v54, v53
	v_fma_f32 v56, -v52, v55, v54
	v_fmac_f32_e32 v55, v56, v53
	v_fma_f32 v52, -v52, v55, v54
	v_div_fmas_f32 v52, v52, v53, v55
	v_div_fixup_f32 v43, v52, v43, 1.0
	v_fma_f32 v43, v43, v57, v39
	v_max_f32_e32 v43, 0xda24260, v43
	v_cmp_gt_f32_e32 vcc, s56, v43
	v_sub_f32_e32 v56, 1.0, v40
	v_add_f32_e32 v45, 1.0, v45
	v_cndmask_b32_e64 v52, 0, 32, vcc
	v_ldexp_f32 v43, v43, v52
	v_log_f32_e32 v43, v43
	v_exp_f32_e32 v47, v47
	v_mul_f32_e32 v52, 0x3f317217, v43
	v_fma_f32 v52, v43, s57, -v52
	v_fmac_f32_e32 v52, 0x3377d1cf, v43
	v_fmac_f32_e32 v52, 0x3f317217, v43
	v_cmp_lt_f32_e64 s[0:1], |v43|, s8
	v_add_f32_e32 v47, 1.0, v47
	s_nop 0
	v_cndmask_b32_e64 v43, v43, v52, s[0:1]
	v_cndmask_b32_e32 v52, 0, v201, vcc
	v_sub_f32_e32 v43, v43, v52
	v_div_scale_f32 v52, s[0:1], v44, v44, 1.0
	v_rcp_f32_e32 v53, v52
	s_nop 0
	v_fma_f32 v54, -v52, v53, 1.0
	v_fmac_f32_e32 v53, v54, v53
	v_div_scale_f32 v54, vcc, 1.0, v44, 1.0
	v_mul_f32_e32 v55, v54, v53
	v_fma_f32 v60, -v52, v55, v54
	v_fmac_f32_e32 v55, v60, v53
	v_fma_f32 v52, -v52, v55, v54
	v_div_fmas_f32 v52, v52, v53, v55
	v_div_fixup_f32 v44, v52, v44, 1.0
	v_fma_f32 v44, v44, v56, v40
	v_max_f32_e32 v44, 0xda24260, v44
	v_cmp_gt_f32_e32 vcc, s56, v44
	v_sub_f32_e32 v55, 1.0, v41
	s_nop 0
	v_cndmask_b32_e64 v52, 0, 32, vcc
	v_ldexp_f32 v44, v44, v52
	v_log_f32_e32 v44, v44
	s_nop 0
	v_mul_f32_e32 v52, 0x3f317217, v44
	v_fma_f32 v52, v44, s57, -v52
	v_fmac_f32_e32 v52, 0x3377d1cf, v44
	v_fmac_f32_e32 v52, 0x3f317217, v44
	v_cmp_lt_f32_e64 s[0:1], |v44|, s8
	s_nop 1
	v_cndmask_b32_e64 v44, v44, v52, s[0:1]
	v_cndmask_b32_e32 v52, 0, v201, vcc
	v_sub_f32_e32 v44, v44, v52
	v_div_scale_f32 v52, s[0:1], v45, v45, 1.0
	v_rcp_f32_e32 v53, v52
	s_nop 0
	v_fma_f32 v54, -v52, v53, 1.0
	v_fmac_f32_e32 v53, v54, v53
	v_div_scale_f32 v54, vcc, 1.0, v45, 1.0
	v_mul_f32_e32 v60, v54, v53
	v_fma_f32 v61, -v52, v60, v54
	v_fmac_f32_e32 v60, v61, v53
	v_fma_f32 v52, -v52, v60, v54
	v_div_fmas_f32 v52, v52, v53, v60
	v_div_fixup_f32 v45, v52, v45, 1.0
	v_fma_f32 v45, v45, v55, v41
	v_max_f32_e32 v45, 0xda24260, v45
	v_cmp_gt_f32_e32 vcc, s56, v45
	s_waitcnt lgkmcnt(0)
; __device__ __forceinline__ float sigmoidf_(float x) { return 1.0f / (1.0f + __expf(-x)); }
; __device__ __forceinline__ void hg_bcum(const Params& p, int l, const u16* Uhg, int t0, int h, float* bc, float* lbs,
;                                         float* tots) {
;     ...
;   for (int k = 0; k < 4; ++k) {
;     const int s = (tid >> 4) + 16 * k, d0 = (tid & 15) * 8;
;     float z[8];
;     unpack8(*(const uint4*)(Uhg + (size_t)(t0 + s) * 2048 + 512 + h * 128 + d0), z);
;     float lf[8];
; #pragma unroll
;     for (int j = 0; j < 8; ++j) {
;       const float lbv = lbs[d0 + j];
;       const float f = lbv + (1.0f - lbv) * sigmoidf_(z[j]);
;       lf[j] = __logf(fmaxf(f, 1e-30f));
;     }
;     *(float4*)(bc + s * BCS + d0) = make_float4(lf[0], lf[1], lf[2], lf[3]);
;     *(float4*)(bc + s * BCS + d0 + 4) = make_float4(lf[4], lf[5], lf[6], lf[7]);
	v_sub_f32_e32 v54, 1.0, v34
	v_cndmask_b32_e64 v52, 0, 32, vcc
	v_ldexp_f32 v45, v45, v52
	v_log_f32_e32 v45, v45
	s_nop 0
	v_mul_f32_e32 v52, 0x3f317217, v45
	v_fma_f32 v52, v45, s57, -v52
	v_fmac_f32_e32 v52, 0x3377d1cf, v45
	v_fmac_f32_e32 v52, 0x3f317217, v45
	v_cmp_lt_f32_e64 s[0:1], |v45|, s8
	s_nop 1
	v_cndmask_b32_e64 v45, v45, v52, s[0:1]
	v_cndmask_b32_e32 v52, 0, v201, vcc
	v_sub_f32_e32 v45, v45, v52
	v_div_scale_f32 v52, s[0:1], v47, v47, 1.0
	v_rcp_f32_e32 v53, v52
	s_nop 0
	v_fma_f32 v60, -v52, v53, 1.0
	v_fmac_f32_e32 v53, v60, v53
	v_div_scale_f32 v60, vcc, 1.0, v47, 1.0
	v_mul_f32_e32 v61, v60, v53
	v_fma_f32 v65, -v52, v61, v60
	v_fmac_f32_e32 v61, v65, v53
	v_fma_f32 v52, -v52, v61, v60
	v_div_fmas_f32 v52, v52, v53, v61
	v_div_fixup_f32 v47, v52, v47, 1.0
	v_fma_f32 v47, v47, v54, v34
	v_max_f32_e32 v47, 0xda24260, v47
	v_cmp_gt_f32_e32 vcc, s56, v47
	v_sub_f32_e32 v53, 1.0, v35
	s_nop 0
	v_cndmask_b32_e64 v52, 0, 32, vcc
	v_ldexp_f32 v47, v47, v52
	v_log_f32_e32 v47, v47
	s_nop 0
	v_mul_f32_e32 v52, 0x3f317217, v47
	v_fma_f32 v52, v47, s57, -v52
	v_fmac_f32_e32 v52, 0x3377d1cf, v47
	v_fmac_f32_e32 v52, 0x3f317217, v47
	v_cmp_lt_f32_e64 s[0:1], |v47|, s8
	s_nop 1
	v_cndmask_b32_e64 v47, v47, v52, s[0:1]
	v_cndmask_b32_e32 v52, 0, v201, vcc
	v_sub_f32_e32 v60, v47, v52
	v_mul_f32_e32 v47, 0xbfb8aa3b, v51
	v_exp_f32_e32 v47, v47
	s_nop 0
	v_add_f32_e32 v47, 1.0, v47
	v_div_scale_f32 v51, s[0:1], v47, v47, 1.0
	v_rcp_f32_e32 v52, v51
	s_nop 0
	v_fma_f32 v61, -v51, v52, 1.0
	v_fmac_f32_e32 v52, v61, v52
	v_div_scale_f32 v61, vcc, 1.0, v47, 1.0
	v_mul_f32_e32 v65, v61, v52
	v_fma_f32 v66, -v51, v65, v61
	v_fmac_f32_e32 v65, v66, v52
	v_fma_f32 v51, -v51, v65, v61
	v_div_fmas_f32 v51, v51, v52, v65
	v_div_fixup_f32 v47, v51, v47, 1.0
	v_fma_f32 v47, v47, v53, v35
	v_max_f32_e32 v47, 0xda24260, v47
	v_cmp_gt_f32_e32 vcc, s56, v47
	v_sub_f32_e32 v52, 1.0, v36
	s_nop 0
	v_cndmask_b32_e64 v51, 0, 32, vcc
	v_ldexp_f32 v47, v47, v51
	v_log_f32_e32 v47, v47
	s_nop 0
	v_mul_f32_e32 v51, 0x3f317217, v47
	v_fma_f32 v51, v47, s57, -v51
	v_fmac_f32_e32 v51, 0x3377d1cf, v47
	v_fmac_f32_e32 v51, 0x3f317217, v47
	v_cmp_lt_f32_e64 s[0:1], |v47|, s8
	s_nop 1
	v_cndmask_b32_e64 v47, v47, v51, s[0:1]
	v_cndmask_b32_e32 v51, 0, v201, vcc
	v_sub_f32_e32 v61, v47, v51
	v_mul_f32_e32 v47, 0xbfb8aa3b, v62
	v_exp_f32_e32 v47, v47
	s_nop 0
	v_add_f32_e32 v47, 1.0, v47
	v_div_scale_f32 v51, s[0:1], v47, v47, 1.0
	v_rcp_f32_e32 v62, v51
	s_nop 0
	v_fma_f32 v65, -v51, v62, 1.0
	v_fmac_f32_e32 v62, v65, v62
	v_div_scale_f32 v65, vcc, 1.0, v47, 1.0
	v_mul_f32_e32 v66, v65, v62
	v_fma_f32 v67, -v51, v66, v65
	v_fmac_f32_e32 v66, v67, v62
	v_fma_f32 v51, -v51, v66, v65
	v_div_fmas_f32 v51, v51, v62, v66
	v_div_fixup_f32 v47, v51, v47, 1.0
	v_fma_f32 v47, v47, v52, v36
	v_max_f32_e32 v47, 0xda24260, v47
	v_cmp_gt_f32_e32 vcc, s56, v47
	s_nop 1
	v_cndmask_b32_e64 v51, 0, 32, vcc
	v_ldexp_f32 v47, v47, v51
	v_log_f32_e32 v47, v47
	s_nop 0
	v_mul_f32_e32 v51, 0x3f317217, v47
	v_fma_f32 v51, v47, s57, -v51
	v_fmac_f32_e32 v51, 0x3377d1cf, v47
	v_fmac_f32_e32 v51, 0x3f317217, v47
	v_cmp_lt_f32_e64 s[0:1], |v47|, s8
	s_nop 1
	v_cndmask_b32_e64 v47, v47, v51, s[0:1]
	v_cndmask_b32_e32 v51, 0, v201, vcc
	v_sub_f32_e32 v62, v47, v51
	v_mul_f32_e32 v47, 0xbfb8aa3b, v63
	v_exp_f32_e32 v47, v47
	v_sub_f32_e32 v51, 1.0, v37
	v_add_f32_e32 v47, 1.0, v47
	v_div_scale_f32 v63, s[0:1], v47, v47, 1.0
	v_rcp_f32_e32 v65, v63
	s_nop 0
	v_fma_f32 v66, -v63, v65, 1.0
	v_fmac_f32_e32 v65, v66, v65
	v_div_scale_f32 v66, vcc, 1.0, v47, 1.0
	v_mul_f32_e32 v67, v66, v65
	v_fma_f32 v68, -v63, v67, v66
	v_fmac_f32_e32 v67, v68, v65
	v_fma_f32 v63, -v63, v67, v66
	v_div_fmas_f32 v63, v63, v65, v67
	v_div_fixup_f32 v47, v63, v47, 1.0
	v_fma_f32 v47, v47, v51, v37
	v_max_f32_e32 v47, 0xda24260, v47
	v_cmp_gt_f32_e32 vcc, s56, v47
	s_nop 1
	v_cndmask_b32_e64 v63, 0, 32, vcc
	v_ldexp_f32 v47, v47, v63
	v_log_f32_e32 v47, v47
	s_nop 0
	v_mul_f32_e32 v63, 0x3f317217, v47
	v_fma_f32 v63, v47, s57, -v63
	v_fmac_f32_e32 v63, 0x3377d1cf, v47
	v_fmac_f32_e32 v63, 0x3f317217, v47
	v_cmp_lt_f32_e64 s[0:1], |v47|, s8
	s_nop 1
	v_cndmask_b32_e64 v47, v47, v63, s[0:1]
	v_cndmask_b32_e32 v63, 0, v201, vcc
	v_sub_f32_e32 v63, v47, v63
	v_mad_u32_u24 v47, v59, s2, v64
	ds_write_b128 v47, v[42:45]
	ds_write_b128 v47, v[60:63] offset:16
	v_or_b32_e32 v42, 16, v46
	v_ashrrev_i32_e32 v43, 31, v42
	v_lshlrev_b64 v[42:43], 12, v[42:43]
	v_lshl_add_u64 v[42:43], s[22:23], 0, v[42:43]
	v_lshl_add_u64 v[42:43], v[42:43], 0, s[58:59]
	v_lshl_add_u64 v[42:43], v[42:43], 0, v[48:49]
	s_waitcnt vmcnt(2)
; __device__ __forceinline__ float sigmoidf_(float x) { return 1.0f / (1.0f + __expf(-x)); }
; __device__ __forceinline__ void hg_bcum(const Params& p, int l, const u16* Uhg, int t0, int h, float* bc, float* lbs,
;                                         float* tots) {
;     ...
;   for (int k = 0; k < 4; ++k) {
;     const int s = (tid >> 4) + 16 * k, d0 = (tid & 15) * 8;
;     float z[8];
;     unpack8(*(const uint4*)(Uhg + (size_t)(t0 + s) * 2048 + 512 + h * 128 + d0), z);
;     float lf[8];
; #pragma unroll
;     for (int j = 0; j < 8; ++j) {
;       const float lbv = lbs[d0 + j];
;       const float f = lbv + (1.0f - lbv) * sigmoidf_(z[j]);
;       lf[j] = __logf(fmaxf(f, 1e-30f));
;     }
;     *(float4*)(bc + s * BCS + d0) = make_float4(lf[0], lf[1], lf[2], lf[3]);
;     *(float4*)(bc + s * BCS + d0 + 4) = make_float4(lf[4], lf[5], lf[6], lf[7]);
	v_mov_b64_e32 v[42:43], v[98:99]
	v_mov_b64_e32 v[44:45], v[100:101]
	v_lshlrev_b32_e32 v61, 16, v42
	v_and_b32_e32 v62, 0xffff0000, v42
	v_mul_f32_e32 v42, 0xbfb8aa3b, v61
	v_exp_f32_e32 v42, v42
	v_lshlrev_b32_e32 v63, 16, v43
	v_and_b32_e32 v64, 0xffff0000, v43
	v_lshlrev_b32_e32 v65, 16, v44
	v_add_f32_e32 v42, 1.0, v42
	v_div_scale_f32 v43, s[0:1], v42, v42, 1.0
	v_and_b32_e32 v66, 0xffff0000, v44
	v_rcp_f32_e32 v44, v43
	v_lshlrev_b32_e32 v60, 16, v45
	v_and_b32_e32 v59, 0xffff0000, v45
	v_mul_f32_e32 v60, 0xbfb8aa3b, v60
	v_fma_f32 v45, -v43, v44, 1.0
	v_fmac_f32_e32 v44, v45, v44
	v_div_scale_f32 v45, vcc, 1.0, v42, 1.0
	v_mul_f32_e32 v61, v45, v44
	v_fma_f32 v67, -v43, v61, v45
	v_fmac_f32_e32 v61, v67, v44
	v_fma_f32 v43, -v43, v61, v45
	v_div_fmas_f32 v43, v43, v44, v61
	v_div_fixup_f32 v42, v43, v42, 1.0
	v_fma_f32 v42, v58, v42, v38
	v_max_f32_e32 v42, 0xda24260, v42
	v_cmp_gt_f32_e32 vcc, s56, v42
	v_exp_f32_e32 v60, v60
	v_mul_f32_e32 v59, 0xbfb8aa3b, v59
	v_cndmask_b32_e64 v43, 0, 32, vcc
	v_ldexp_f32 v42, v42, v43
	v_log_f32_e32 v42, v42
	v_add_f32_e32 v60, 1.0, v60
	v_exp_f32_e32 v59, v59
	v_mul_f32_e32 v43, 0x3f317217, v42
	v_fma_f32 v43, v42, s57, -v43
	v_fmac_f32_e32 v43, 0x3377d1cf, v42
	v_fmac_f32_e32 v43, 0x3f317217, v42
	v_cmp_lt_f32_e64 s[0:1], |v42|, s8
	v_add_f32_e32 v59, 1.0, v59
	s_nop 0
	v_cndmask_b32_e64 v42, v42, v43, s[0:1]
	v_cndmask_b32_e32 v43, 0, v201, vcc
	v_sub_f32_e32 v42, v42, v43
	v_mul_f32_e32 v43, 0xbfb8aa3b, v62
	v_exp_f32_e32 v43, v43
	s_nop 0
	v_add_f32_e32 v43, 1.0, v43
	v_div_scale_f32 v44, s[0:1], v43, v43, 1.0
	v_rcp_f32_e32 v45, v44
	s_nop 0
	v_fma_f32 v61, -v44, v45, 1.0
	v_fmac_f32_e32 v45, v61, v45
	v_div_scale_f32 v61, vcc, 1.0, v43, 1.0
	v_mul_f32_e32 v62, v61, v45
	v_fma_f32 v67, -v44, v62, v61
	v_fmac_f32_e32 v62, v67, v45
	v_fma_f32 v44, -v44, v62, v61
	v_div_fmas_f32 v44, v44, v45, v62
	v_div_fixup_f32 v43, v44, v43, 1.0
	v_fma_f32 v43, v57, v43, v39
	v_max_f32_e32 v43, 0xda24260, v43
	v_cmp_gt_f32_e32 vcc, s56, v43
	s_nop 1
	v_cndmask_b32_e64 v44, 0, 32, vcc
	v_ldexp_f32 v43, v43, v44
	v_log_f32_e32 v43, v43
	s_nop 0
	v_mul_f32_e32 v44, 0x3f317217, v43
	v_fma_f32 v44, v43, s57, -v44
	v_fmac_f32_e32 v44, 0x3377d1cf, v43
	v_fmac_f32_e32 v44, 0x3f317217, v43
	v_cmp_lt_f32_e64 s[0:1], |v43|, s8
	s_nop 1
	v_cndmask_b32_e64 v43, v43, v44, s[0:1]
	v_cndmask_b32_e32 v44, 0, v201, vcc
	v_sub_f32_e32 v43, v43, v44
	v_mul_f32_e32 v44, 0xbfb8aa3b, v63
	v_exp_f32_e32 v44, v44
	s_nop 0
	v_add_f32_e32 v44, 1.0, v44
	v_div_scale_f32 v45, s[0:1], v44, v44, 1.0
	v_rcp_f32_e32 v61, v45
	s_nop 0
	v_fma_f32 v62, -v45, v61, 1.0
	v_fmac_f32_e32 v61, v62, v61
	v_div_scale_f32 v62, vcc, 1.0, v44, 1.0
	v_mul_f32_e32 v63, v62, v61
	v_fma_f32 v67, -v45, v63, v62
	v_fmac_f32_e32 v63, v67, v61
	v_fma_f32 v45, -v45, v63, v62
	v_div_fmas_f32 v45, v45, v61, v63
	v_div_fixup_f32 v44, v45, v44, 1.0
	v_fma_f32 v44, v56, v44, v40
	v_max_f32_e32 v44, 0xda24260, v44
	v_cmp_gt_f32_e32 vcc, s56, v44
	s_nop 1
	v_cndmask_b32_e64 v45, 0, 32, vcc
	v_ldexp_f32 v44, v44, v45
	v_log_f32_e32 v44, v44
	s_nop 0
	v_mul_f32_e32 v45, 0x3f317217, v44
	v_fma_f32 v45, v44, s57, -v45
	v_fmac_f32_e32 v45, 0x3377d1cf, v44
	v_fmac_f32_e32 v45, 0x3f317217, v44
	v_cmp_lt_f32_e64 s[0:1], |v44|, s8
	s_nop 1
	v_cndmask_b32_e64 v44, v44, v45, s[0:1]
	v_cndmask_b32_e32 v45, 0, v201, vcc
	v_sub_f32_e32 v44, v44, v45
	v_mul_f32_e32 v45, 0xbfb8aa3b, v64
	v_exp_f32_e32 v45, v45
	s_nop 0
	v_add_f32_e32 v45, 1.0, v45
	v_div_scale_f32 v61, s[0:1], v45, v45, 1.0
	v_rcp_f32_e32 v62, v61
	s_nop 0
	v_fma_f32 v63, -v61, v62, 1.0
	v_fmac_f32_e32 v62, v63, v62
	v_div_scale_f32 v63, vcc, 1.0, v45, 1.0
	v_mul_f32_e32 v64, v63, v62
	v_fma_f32 v67, -v61, v64, v63
	v_fmac_f32_e32 v64, v67, v62
	v_fma_f32 v61, -v61, v64, v63
	v_div_fmas_f32 v61, v61, v62, v64
	v_div_fixup_f32 v45, v61, v45, 1.0
	v_fma_f32 v45, v55, v45, v41
	v_max_f32_e32 v45, 0xda24260, v45
	v_cmp_gt_f32_e32 vcc, s56, v45
	s_nop 1
	v_cndmask_b32_e64 v61, 0, 32, vcc
	v_ldexp_f32 v45, v45, v61
	v_log_f32_e32 v45, v45
	s_nop 0
	v_mul_f32_e32 v61, 0x3f317217, v45
	v_fma_f32 v61, v45, s57, -v61
	v_fmac_f32_e32 v61, 0x3377d1cf, v45
	v_fmac_f32_e32 v61, 0x3f317217, v45
	v_cmp_lt_f32_e64 s[0:1], |v45|, s8
	s_nop 1
	v_cndmask_b32_e64 v45, v45, v61, s[0:1]
	v_cndmask_b32_e32 v61, 0, v201, vcc
	v_sub_f32_e32 v45, v45, v61
	v_mul_f32_e32 v61, 0xbfb8aa3b, v65
	v_exp_f32_e32 v61, v61
	s_nop 0
	v_add_f32_e32 v61, 1.0, v61
	v_div_scale_f32 v62, s[0:1], v61, v61, 1.0
	v_rcp_f32_e32 v63, v62
	s_nop 0
	v_fma_f32 v64, -v62, v63, 1.0
	v_fmac_f32_e32 v63, v64, v63
	v_div_scale_f32 v64, vcc, 1.0, v61, 1.0
	v_mul_f32_e32 v65, v64, v63
	v_fma_f32 v67, -v62, v65, v64
	v_fmac_f32_e32 v65, v67, v63
	v_fma_f32 v62, -v62, v65, v64
	v_div_fmas_f32 v62, v62, v63, v65
	v_div_fixup_f32 v61, v62, v61, 1.0
	v_fma_f32 v61, v54, v61, v34
	v_max_f32_e32 v61, 0xda24260, v61
	v_cmp_gt_f32_e32 vcc, s56, v61
	s_nop 1
	v_cndmask_b32_e64 v62, 0, 32, vcc
	v_ldexp_f32 v61, v61, v62
	v_log_f32_e32 v61, v61
	s_nop 0
	v_mul_f32_e32 v62, 0x3f317217, v61
	v_fma_f32 v62, v61, s57, -v62
	v_fmac_f32_e32 v62, 0x3377d1cf, v61
	v_fmac_f32_e32 v62, 0x3f317217, v61
	v_cmp_lt_f32_e64 s[0:1], |v61|, s8
	s_nop 1
	v_cndmask_b32_e64 v61, v61, v62, s[0:1]
	v_cndmask_b32_e32 v62, 0, v201, vcc
	v_sub_f32_e32 v62, v61, v62
	v_mul_f32_e32 v61, 0xbfb8aa3b, v66
	v_exp_f32_e32 v61, v61
	s_nop 0
	v_add_f32_e32 v61, 1.0, v61
	v_div_scale_f32 v63, s[0:1], v61, v61, 1.0
	v_rcp_f32_e32 v64, v63
	s_nop 0
	v_fma_f32 v65, -v63, v64, 1.0
	v_fmac_f32_e32 v64, v65, v64
	v_div_scale_f32 v65, vcc, 1.0, v61, 1.0
	v_mul_f32_e32 v66, v65, v64
	v_fma_f32 v67, -v63, v66, v65
; __device__ __forceinline__ float sigmoidf_(float x) { return 1.0f / (1.0f + __expf(-x)); }
; __device__ __forceinline__ void hg_bcum(const Params& p, int l, const u16* Uhg, int t0, int h, float* bc, float* lbs,
;                                         float* tots) {
;     ...
;   for (int k = 0; k < 4; ++k) {
;     const int s = (tid >> 4) + 16 * k, d0 = (tid & 15) * 8;
;     float z[8];
;     unpack8(*(const uint4*)(Uhg + (size_t)(t0 + s) * 2048 + 512 + h * 128 + d0), z);
;     float lf[8];
; #pragma unroll
;     for (int j = 0; j < 8; ++j) {
;       const float lbv = lbs[d0 + j];
;       const float f = lbv + (1.0f - lbv) * sigmoidf_(z[j]);
;       lf[j] = __logf(fmaxf(f, 1e-30f));
;     }
;     *(float4*)(bc + s * BCS + d0) = make_float4(lf[0], lf[1], lf[2], lf[3]);
;     *(float4*)(bc + s * BCS + d0 + 4) = make_float4(lf[4], lf[5], lf[6], lf[7]);
	v_fmac_f32_e32 v66, v67, v64
	v_fma_f32 v63, -v63, v66, v65
	v_div_fmas_f32 v63, v63, v64, v66
	v_div_fixup_f32 v61, v63, v61, 1.0
	v_fma_f32 v61, v53, v61, v35
	v_max_f32_e32 v61, 0xda24260, v61
	v_cmp_gt_f32_e32 vcc, s56, v61
	s_nop 1
	v_cndmask_b32_e64 v63, 0, 32, vcc
	v_ldexp_f32 v61, v61, v63
	v_log_f32_e32 v61, v61
	s_nop 0
	v_mul_f32_e32 v63, 0x3f317217, v61
	v_fma_f32 v63, v61, s57, -v63
	v_fmac_f32_e32 v63, 0x3377d1cf, v61
	v_fmac_f32_e32 v63, 0x3f317217, v61
	v_cmp_lt_f32_e64 s[0:1], |v61|, s8
	s_nop 1
	v_cndmask_b32_e64 v61, v61, v63, s[0:1]
	v_cndmask_b32_e32 v63, 0, v201, vcc
	v_sub_f32_e32 v63, v61, v63
	v_div_scale_f32 v61, s[0:1], v60, v60, 1.0
	v_rcp_f32_e32 v64, v61
	s_nop 0
	v_fma_f32 v65, -v61, v64, 1.0
	v_fmac_f32_e32 v64, v65, v64
	v_div_scale_f32 v65, vcc, 1.0, v60, 1.0
	v_mul_f32_e32 v66, v65, v64
	v_fma_f32 v67, -v61, v66, v65
	v_fmac_f32_e32 v66, v67, v64
	v_fma_f32 v61, -v61, v66, v65
	v_div_fmas_f32 v61, v61, v64, v66
	v_div_fixup_f32 v60, v61, v60, 1.0
	v_fma_f32 v60, v52, v60, v36
	v_max_f32_e32 v60, 0xda24260, v60
	v_cmp_gt_f32_e32 vcc, s56, v60
	s_nop 1
	v_cndmask_b32_e64 v61, 0, 32, vcc
	v_ldexp_f32 v60, v60, v61
	v_log_f32_e32 v60, v60
	s_nop 0
	v_mul_f32_e32 v61, 0x3f317217, v60
	v_fma_f32 v61, v60, s57, -v61
	v_fmac_f32_e32 v61, 0x3377d1cf, v60
	v_fmac_f32_e32 v61, 0x3f317217, v60
	v_cmp_lt_f32_e64 s[0:1], |v60|, s8
	s_nop 1
	v_cndmask_b32_e64 v60, v60, v61, s[0:1]
	v_cndmask_b32_e32 v61, 0, v201, vcc
	v_sub_f32_e32 v64, v60, v61
	v_div_scale_f32 v60, s[0:1], v59, v59, 1.0
	v_rcp_f32_e32 v61, v60
	s_nop 0
	v_fma_f32 v65, -v60, v61, 1.0
	v_fmac_f32_e32 v61, v65, v61
	v_div_scale_f32 v65, vcc, 1.0, v59, 1.0
	v_mul_f32_e32 v66, v65, v61
	v_fma_f32 v67, -v60, v66, v65
	v_fmac_f32_e32 v66, v67, v61
	v_fma_f32 v60, -v60, v66, v65
	v_div_fmas_f32 v60, v60, v61, v66
	v_div_fixup_f32 v59, v60, v59, 1.0
	v_fma_f32 v59, v51, v59, v37
	v_max_f32_e32 v59, 0xda24260, v59
	v_cmp_gt_f32_e32 vcc, s56, v59
	s_nop 1
	v_cndmask_b32_e64 v60, 0, 32, vcc
	v_ldexp_f32 v59, v59, v60
	v_log_f32_e32 v59, v59
	s_nop 0
	v_mul_f32_e32 v60, 0x3f317217, v59
	v_fma_f32 v60, v59, s57, -v60
	v_fmac_f32_e32 v60, 0x3377d1cf, v59
	v_fmac_f32_e32 v60, 0x3f317217, v59
	v_cmp_lt_f32_e64 s[0:1], |v59|, s8
	s_nop 1
	v_cndmask_b32_e64 v59, v59, v60, s[0:1]
	v_cndmask_b32_e32 v60, 0, v201, vcc
	v_sub_f32_e32 v65, v59, v60
	ds_write_b128 v47, v[42:45] offset:8448
	ds_write_b128 v47, v[62:65] offset:8464
	v_or_b32_e32 v42, 32, v46
	v_ashrrev_i32_e32 v43, 31, v42
	v_lshlrev_b64 v[42:43], 12, v[42:43]
	v_lshl_add_u64 v[42:43], s[22:23], 0, v[42:43]
	v_lshl_add_u64 v[42:43], v[42:43], 0, s[58:59]
	v_lshl_add_u64 v[42:43], v[42:43], 0, v[48:49]
	s_waitcnt vmcnt(1)
	v_mov_b64_e32 v[42:43], v[102:103]
	v_mov_b64_e32 v[44:45], v[104:105]
	v_lshlrev_b32_e32 v59, 16, v42
	v_and_b32_e32 v60, 0xffff0000, v42
	v_mul_f32_e32 v42, 0xbfb8aa3b, v59
	v_exp_f32_e32 v42, v42
	v_lshlrev_b32_e32 v61, 16, v43
	v_and_b32_e32 v62, 0xffff0000, v43
	v_lshlrev_b32_e32 v63, 16, v44
	v_add_f32_e32 v42, 1.0, v42
	v_div_scale_f32 v43, s[0:1], v42, v42, 1.0
	v_and_b32_e32 v64, 0xffff0000, v44
	v_rcp_f32_e32 v44, v43
	v_lshlrev_b32_e32 v65, 16, v45
	v_and_b32_e32 v66, 0xffff0000, v45
	v_fma_f32 v45, -v43, v44, 1.0
	v_fmac_f32_e32 v44, v45, v44
	v_div_scale_f32 v45, vcc, 1.0, v42, 1.0
	v_mul_f32_e32 v59, v45, v44
	v_fma_f32 v67, -v43, v59, v45
	v_fmac_f32_e32 v59, v67, v44
	v_fma_f32 v43, -v43, v59, v45
	v_div_fmas_f32 v43, v43, v44, v59
	v_div_fixup_f32 v42, v43, v42, 1.0
	v_fma_f32 v42, v58, v42, v38
	v_max_f32_e32 v42, 0xda24260, v42
	v_cmp_gt_f32_e32 vcc, s56, v42
	s_nop 1
	v_cndmask_b32_e64 v43, 0, 32, vcc
	v_ldexp_f32 v42, v42, v43
	v_log_f32_e32 v42, v42
	s_nop 0
	v_mul_f32_e32 v43, 0x3f317217, v42
	v_fma_f32 v43, v42, s57, -v43
	v_fmac_f32_e32 v43, 0x3377d1cf, v42
	v_fmac_f32_e32 v43, 0x3f317217, v42
	v_cmp_lt_f32_e64 s[0:1], |v42|, s8
	s_nop 1
	v_cndmask_b32_e64 v42, v42, v43, s[0:1]
	v_cndmask_b32_e32 v43, 0, v201, vcc
	v_sub_f32_e32 v42, v42, v43
	v_mul_f32_e32 v43, 0xbfb8aa3b, v60
	v_exp_f32_e32 v43, v43
	s_nop 0
	v_add_f32_e32 v43, 1.0, v43
	v_div_scale_f32 v44, s[0:1], v43, v43, 1.0
	v_rcp_f32_e32 v45, v44
	s_nop 0
	v_fma_f32 v59, -v44, v45, 1.0
	v_fmac_f32_e32 v45, v59, v45
	v_div_scale_f32 v59, vcc, 1.0, v43, 1.0
	v_mul_f32_e32 v60, v59, v45
	v_fma_f32 v67, -v44, v60, v59
	v_fmac_f32_e32 v60, v67, v45
	v_fma_f32 v44, -v44, v60, v59
	v_div_fmas_f32 v44, v44, v45, v60
	v_div_fixup_f32 v43, v44, v43, 1.0
	v_fma_f32 v43, v57, v43, v39
	v_max_f32_e32 v43, 0xda24260, v43
	v_cmp_gt_f32_e32 vcc, s56, v43
	s_nop 1
	v_cndmask_b32_e64 v44, 0, 32, vcc
	v_ldexp_f32 v43, v43, v44
	v_log_f32_e32 v43, v43
	s_nop 0
	v_mul_f32_e32 v44, 0x3f317217, v43
	v_fma_f32 v44, v43, s57, -v44
	v_fmac_f32_e32 v44, 0x3377d1cf, v43
	v_fmac_f32_e32 v44, 0x3f317217, v43
	v_cmp_lt_f32_e64 s[0:1], |v43|, s8
	s_nop 1
	v_cndmask_b32_e64 v43, v43, v44, s[0:1]
	v_cndmask_b32_e32 v44, 0, v201, vcc
	v_sub_f32_e32 v43, v43, v44
	v_mul_f32_e32 v44, 0xbfb8aa3b, v61
	v_exp_f32_e32 v44, v44
	s_nop 0
	v_add_f32_e32 v44, 1.0, v44
	v_div_scale_f32 v45, s[0:1], v44, v44, 1.0
	v_rcp_f32_e32 v59, v45
	s_nop 0
	v_fma_f32 v60, -v45, v59, 1.0
	v_fmac_f32_e32 v59, v60, v59
	v_div_scale_f32 v60, vcc, 1.0, v44, 1.0
	v_mul_f32_e32 v61, v60, v59
	v_fma_f32 v67, -v45, v61, v60
	v_fmac_f32_e32 v61, v67, v59
	v_fma_f32 v45, -v45, v61, v60
	v_div_fmas_f32 v45, v45, v59, v61
	v_div_fixup_f32 v44, v45, v44, 1.0
	v_fma_f32 v44, v56, v44, v40
	v_max_f32_e32 v44, 0xda24260, v44
	v_cmp_gt_f32_e32 vcc, s56, v44
	s_nop 1
	v_cndmask_b32_e64 v45, 0, 32, vcc
	v_ldexp_f32 v44, v44, v45
	v_log_f32_e32 v44, v44
	s_nop 0
	v_mul_f32_e32 v45, 0x3f317217, v44
; __device__ __forceinline__ float sigmoidf_(float x) { return 1.0f / (1.0f + __expf(-x)); }
; __device__ __forceinline__ void hg_bcum(const Params& p, int l, const u16* Uhg, int t0, int h, float* bc, float* lbs,
;                                         float* tots) {
;     ...
;   for (int k = 0; k < 4; ++k) {
;     const int s = (tid >> 4) + 16 * k, d0 = (tid & 15) * 8;
;     float z[8];
;     unpack8(*(const uint4*)(Uhg + (size_t)(t0 + s) * 2048 + 512 + h * 128 + d0), z);
;     float lf[8];
; #pragma unroll
;     for (int j = 0; j < 8; ++j) {
;       const float lbv = lbs[d0 + j];
;       const float f = lbv + (1.0f - lbv) * sigmoidf_(z[j]);
;       lf[j] = __logf(fmaxf(f, 1e-30f));
;     }
;     *(float4*)(bc + s * BCS + d0) = make_float4(lf[0], lf[1], lf[2], lf[3]);
;     *(float4*)(bc + s * BCS + d0 + 4) = make_float4(lf[4], lf[5], lf[6], lf[7]);
	v_fma_f32 v45, v44, s57, -v45
	v_fmac_f32_e32 v45, 0x3377d1cf, v44
	v_fmac_f32_e32 v45, 0x3f317217, v44
	v_cmp_lt_f32_e64 s[0:1], |v44|, s8
	s_nop 1
	v_cndmask_b32_e64 v44, v44, v45, s[0:1]
	v_cndmask_b32_e32 v45, 0, v201, vcc
	v_sub_f32_e32 v44, v44, v45
	v_mul_f32_e32 v45, 0xbfb8aa3b, v62
	v_exp_f32_e32 v45, v45
	s_nop 0
	v_add_f32_e32 v45, 1.0, v45
	v_div_scale_f32 v59, s[0:1], v45, v45, 1.0
	v_rcp_f32_e32 v60, v59
	s_nop 0
	v_fma_f32 v61, -v59, v60, 1.0
	v_fmac_f32_e32 v60, v61, v60
	v_div_scale_f32 v61, vcc, 1.0, v45, 1.0
	v_mul_f32_e32 v62, v61, v60
	v_fma_f32 v67, -v59, v62, v61
	v_fmac_f32_e32 v62, v67, v60
	v_fma_f32 v59, -v59, v62, v61
	v_div_fmas_f32 v59, v59, v60, v62
	v_div_fixup_f32 v45, v59, v45, 1.0
	v_fma_f32 v45, v55, v45, v41
	v_max_f32_e32 v45, 0xda24260, v45
	v_cmp_gt_f32_e32 vcc, s56, v45
	s_nop 1
	v_cndmask_b32_e64 v59, 0, 32, vcc
	v_ldexp_f32 v45, v45, v59
	v_log_f32_e32 v45, v45
	s_nop 0
	v_mul_f32_e32 v59, 0x3f317217, v45
	v_fma_f32 v59, v45, s57, -v59
	v_fmac_f32_e32 v59, 0x3377d1cf, v45
	v_fmac_f32_e32 v59, 0x3f317217, v45
	v_cmp_lt_f32_e64 s[0:1], |v45|, s8
	s_nop 1
	v_cndmask_b32_e64 v45, v45, v59, s[0:1]
	v_cndmask_b32_e32 v59, 0, v201, vcc
	v_sub_f32_e32 v45, v45, v59
	v_mul_f32_e32 v59, 0xbfb8aa3b, v63
	v_exp_f32_e32 v59, v59
	s_nop 0
	v_add_f32_e32 v59, 1.0, v59
	v_div_scale_f32 v60, s[0:1], v59, v59, 1.0
	v_rcp_f32_e32 v61, v60
	s_nop 0
	v_fma_f32 v62, -v60, v61, 1.0
	v_fmac_f32_e32 v61, v62, v61
	v_div_scale_f32 v62, vcc, 1.0, v59, 1.0
	v_mul_f32_e32 v63, v62, v61
	v_fma_f32 v67, -v60, v63, v62
	v_fmac_f32_e32 v63, v67, v61
	v_fma_f32 v60, -v60, v63, v62
	v_div_fmas_f32 v60, v60, v61, v63
	v_div_fixup_f32 v59, v60, v59, 1.0
	v_fma_f32 v59, v54, v59, v34
	v_max_f32_e32 v59, 0xda24260, v59
	v_cmp_gt_f32_e32 vcc, s56, v59
	s_nop 1
	v_cndmask_b32_e64 v60, 0, 32, vcc
	v_ldexp_f32 v59, v59, v60
	v_log_f32_e32 v59, v59
	s_nop 0
	v_mul_f32_e32 v60, 0x3f317217, v59
	v_fma_f32 v60, v59, s57, -v60
	v_fmac_f32_e32 v60, 0x3377d1cf, v59
	v_fmac_f32_e32 v60, 0x3f317217, v59
	v_cmp_lt_f32_e64 s[0:1], |v59|, s8
	s_nop 1
	v_cndmask_b32_e64 v59, v59, v60, s[0:1]
	v_cndmask_b32_e32 v60, 0, v201, vcc
	v_sub_f32_e32 v60, v59, v60
	v_mul_f32_e32 v59, 0xbfb8aa3b, v64
	v_exp_f32_e32 v59, v59
	s_nop 0
	v_add_f32_e32 v59, 1.0, v59
	v_div_scale_f32 v61, s[0:1], v59, v59, 1.0
	v_rcp_f32_e32 v62, v61
	s_nop 0
	v_fma_f32 v63, -v61, v62, 1.0
	v_fmac_f32_e32 v62, v63, v62
	v_div_scale_f32 v63, vcc, 1.0, v59, 1.0
	v_mul_f32_e32 v64, v63, v62
	v_fma_f32 v67, -v61, v64, v63
	v_fmac_f32_e32 v64, v67, v62
	v_fma_f32 v61, -v61, v64, v63
	v_div_fmas_f32 v61, v61, v62, v64
	v_div_fixup_f32 v59, v61, v59, 1.0
	v_fma_f32 v59, v53, v59, v35
	v_max_f32_e32 v59, 0xda24260, v59
	v_cmp_gt_f32_e32 vcc, s56, v59
	s_nop 1
	v_cndmask_b32_e64 v61, 0, 32, vcc
	v_ldexp_f32 v59, v59, v61
	v_log_f32_e32 v59, v59
	s_nop 0
	v_mul_f32_e32 v61, 0x3f317217, v59
	v_fma_f32 v61, v59, s57, -v61
	v_fmac_f32_e32 v61, 0x3377d1cf, v59
	v_fmac_f32_e32 v61, 0x3f317217, v59
	v_cmp_lt_f32_e64 s[0:1], |v59|, s8
	s_nop 1
	v_cndmask_b32_e64 v59, v59, v61, s[0:1]
	v_cndmask_b32_e32 v61, 0, v201, vcc
	v_sub_f32_e32 v61, v59, v61
	v_mul_f32_e32 v59, 0xbfb8aa3b, v65
	v_exp_f32_e32 v59, v59
	s_nop 0
	v_add_f32_e32 v59, 1.0, v59
	v_div_scale_f32 v62, s[0:1], v59, v59, 1.0
	v_rcp_f32_e32 v63, v62
	s_nop 0
	v_fma_f32 v64, -v62, v63, 1.0
	v_fmac_f32_e32 v63, v64, v63
	v_div_scale_f32 v64, vcc, 1.0, v59, 1.0
	v_mul_f32_e32 v65, v64, v63
	v_fma_f32 v67, -v62, v65, v64
	v_fmac_f32_e32 v65, v67, v63
	v_fma_f32 v62, -v62, v65, v64
	v_div_fmas_f32 v62, v62, v63, v65
	v_div_fixup_f32 v59, v62, v59, 1.0
	v_fma_f32 v59, v52, v59, v36
	v_max_f32_e32 v59, 0xda24260, v59
	v_cmp_gt_f32_e32 vcc, s56, v59
	s_nop 1
	v_cndmask_b32_e64 v62, 0, 32, vcc
	v_ldexp_f32 v59, v59, v62
	v_log_f32_e32 v59, v59
	s_nop 0
	v_mul_f32_e32 v62, 0x3f317217, v59
	v_fma_f32 v62, v59, s57, -v62
	v_fmac_f32_e32 v62, 0x3377d1cf, v59
	v_fmac_f32_e32 v62, 0x3f317217, v59
	v_cmp_lt_f32_e64 s[0:1], |v59|, s8
	s_nop 1
	v_cndmask_b32_e64 v59, v59, v62, s[0:1]
	v_cndmask_b32_e32 v62, 0, v201, vcc
	v_sub_f32_e32 v62, v59, v62
	v_mul_f32_e32 v59, 0xbfb8aa3b, v66
	v_exp_f32_e32 v59, v59
	s_nop 0
	v_add_f32_e32 v59, 1.0, v59
	v_div_scale_f32 v63, s[0:1], v59, v59, 1.0
	v_rcp_f32_e32 v64, v63
	s_nop 0
	v_fma_f32 v65, -v63, v64, 1.0
	v_fmac_f32_e32 v64, v65, v64
	v_div_scale_f32 v65, vcc, 1.0, v59, 1.0
	v_mul_f32_e32 v66, v65, v64
	v_fma_f32 v67, -v63, v66, v65
	v_fmac_f32_e32 v66, v67, v64
	v_fma_f32 v63, -v63, v66, v65
	v_div_fmas_f32 v63, v63, v64, v66
	v_div_fixup_f32 v59, v63, v59, 1.0
	v_fma_f32 v59, v51, v59, v37
	v_max_f32_e32 v59, 0xda24260, v59
	v_cmp_gt_f32_e32 vcc, s56, v59
	s_nop 1
	v_cndmask_b32_e64 v63, 0, 32, vcc
	v_ldexp_f32 v59, v59, v63
	v_log_f32_e32 v59, v59
	s_nop 0
	v_mul_f32_e32 v63, 0x3f317217, v59
	v_fma_f32 v63, v59, s57, -v63
	v_fmac_f32_e32 v63, 0x3377d1cf, v59
	v_fmac_f32_e32 v63, 0x3f317217, v59
	v_cmp_lt_f32_e64 s[0:1], |v59|, s8
	s_nop 1
	v_cndmask_b32_e64 v59, v59, v63, s[0:1]
	v_cndmask_b32_e32 v63, 0, v201, vcc
	v_sub_f32_e32 v63, v59, v63
	ds_write_b128 v47, v[42:45] offset:16896
	ds_write_b128 v47, v[60:63] offset:16912
	v_or_b32_e32 v42, 48, v46
	v_ashrrev_i32_e32 v43, 31, v42
	v_lshlrev_b64 v[42:43], 12, v[42:43]
	v_lshl_add_u64 v[42:43], s[22:23], 0, v[42:43]
	v_lshl_add_u64 v[42:43], v[42:43], 0, s[58:59]
	v_lshl_add_u64 v[42:43], v[42:43], 0, v[48:49]
	s_waitcnt vmcnt(0)
; __device__ __forceinline__ float sigmoidf_(float x) { return 1.0f / (1.0f + __expf(-x)); }
; __device__ __forceinline__ void hg_bcum(const Params& p, int l, const u16* Uhg, int t0, int h, float* bc, float* lbs,
;                                         float* tots) {
;     ...
;   for (int k = 0; k < 4; ++k) {
;     const int s = (tid >> 4) + 16 * k, d0 = (tid & 15) * 8;
;     float z[8];
;     unpack8(*(const uint4*)(Uhg + (size_t)(t0 + s) * 2048 + 512 + h * 128 + d0), z);
;     float lf[8];
; #pragma unroll
;     for (int j = 0; j < 8; ++j) {
;       const float lbv = lbs[d0 + j];
;       const float f = lbv + (1.0f - lbv) * sigmoidf_(z[j]);
;       lf[j] = __logf(fmaxf(f, 1e-30f));
;     }
;     *(float4*)(bc + s * BCS + d0) = make_float4(lf[0], lf[1], lf[2], lf[3]);
;     *(float4*)(bc + s * BCS + d0 + 4) = make_float4(lf[4], lf[5], lf[6], lf[7]);
	v_mov_b64_e32 v[42:43], v[106:107]
	v_mov_b64_e32 v[44:45], v[108:109]
	v_lshlrev_b32_e32 v46, 16, v42
	v_and_b32_e32 v48, 0xffff0000, v42
	v_lshlrev_b32_e32 v49, 16, v43
	v_and_b32_e32 v59, 0xffff0000, v43
	v_lshlrev_b32_e32 v43, 16, v45
	v_and_b32_e32 v42, 0xffff0000, v45
	v_mul_f32_e32 v45, 0xbfb8aa3b, v46
	v_exp_f32_e32 v45, v45
	v_lshlrev_b32_e32 v60, 16, v44
	v_and_b32_e32 v44, 0xffff0000, v44
	v_mul_f32_e32 v44, 0xbfb8aa3b, v44
	v_add_f32_e32 v45, 1.0, v45
	v_div_scale_f32 v46, s[0:1], v45, v45, 1.0
	v_rcp_f32_e32 v61, v46
	v_exp_f32_e32 v44, v44
	v_mul_f32_e32 v43, 0xbfb8aa3b, v43
	v_exp_f32_e32 v43, v43
	v_fma_f32 v62, -v46, v61, 1.0
	v_fmac_f32_e32 v61, v62, v61
	v_div_scale_f32 v62, vcc, 1.0, v45, 1.0
	v_mul_f32_e32 v63, v62, v61
	v_fma_f32 v64, -v46, v63, v62
	v_fmac_f32_e32 v63, v64, v61
	v_fma_f32 v46, -v46, v63, v62
	v_div_fmas_f32 v46, v46, v61, v63
	v_div_fixup_f32 v45, v46, v45, 1.0
	v_fma_f32 v38, v58, v45, v38
	v_max_f32_e32 v38, 0xda24260, v38
	v_cmp_gt_f32_e32 vcc, s56, v38
	v_add_f32_e32 v44, 1.0, v44
	v_add_f32_e32 v43, 1.0, v43
	v_cndmask_b32_e64 v45, 0, 32, vcc
	v_ldexp_f32 v38, v38, v45
	v_log_f32_e32 v38, v38
	v_mul_f32_e32 v42, 0xbfb8aa3b, v42
	v_exp_f32_e32 v42, v42
	v_mul_f32_e32 v45, 0x3f317217, v38
	v_fma_f32 v45, v38, s57, -v45
	v_fmac_f32_e32 v45, 0x3377d1cf, v38
	v_fmac_f32_e32 v45, 0x3f317217, v38
	v_cmp_lt_f32_e64 s[0:1], |v38|, s8
	v_add_f32_e32 v42, 1.0, v42
	s_nop 0
	v_cndmask_b32_e64 v38, v38, v45, s[0:1]
	v_cndmask_b32_e32 v45, 0, v201, vcc
	v_sub_f32_e32 v38, v38, v45
	v_mul_f32_e32 v45, 0xbfb8aa3b, v48
	v_exp_f32_e32 v45, v45
	s_nop 0
	v_add_f32_e32 v45, 1.0, v45
	v_div_scale_f32 v46, s[0:1], v45, v45, 1.0
	v_rcp_f32_e32 v48, v46
	s_nop 0
	v_fma_f32 v58, -v46, v48, 1.0
	v_fmac_f32_e32 v48, v58, v48
	v_div_scale_f32 v58, vcc, 1.0, v45, 1.0
	v_mul_f32_e32 v61, v58, v48
	v_fma_f32 v62, -v46, v61, v58
	v_fmac_f32_e32 v61, v62, v48
	v_fma_f32 v46, -v46, v61, v58
	v_div_fmas_f32 v46, v46, v48, v61
	v_div_fixup_f32 v45, v46, v45, 1.0
	v_fma_f32 v39, v57, v45, v39
	v_max_f32_e32 v39, 0xda24260, v39
	v_cmp_gt_f32_e32 vcc, s56, v39
	s_nop 1
	v_cndmask_b32_e64 v45, 0, 32, vcc
	v_ldexp_f32 v39, v39, v45
	v_log_f32_e32 v39, v39
	s_nop 0
	v_mul_f32_e32 v45, 0x3f317217, v39
	v_fma_f32 v45, v39, s57, -v45
	v_fmac_f32_e32 v45, 0x3377d1cf, v39
	v_fmac_f32_e32 v45, 0x3f317217, v39
	v_cmp_lt_f32_e64 s[0:1], |v39|, s8
	s_nop 1
	v_cndmask_b32_e64 v39, v39, v45, s[0:1]
	v_cndmask_b32_e32 v45, 0, v201, vcc
	v_sub_f32_e32 v39, v39, v45
	v_mul_f32_e32 v45, 0xbfb8aa3b, v49
	v_exp_f32_e32 v45, v45
	s_nop 0
	v_add_f32_e32 v45, 1.0, v45
	v_div_scale_f32 v46, s[0:1], v45, v45, 1.0
	v_rcp_f32_e32 v48, v46
	s_nop 0
	v_fma_f32 v49, -v46, v48, 1.0
	v_fmac_f32_e32 v48, v49, v48
	v_div_scale_f32 v49, vcc, 1.0, v45, 1.0
	v_mul_f32_e32 v57, v49, v48
	v_fma_f32 v58, -v46, v57, v49
	v_fmac_f32_e32 v57, v58, v48
	v_fma_f32 v46, -v46, v57, v49
	v_div_fmas_f32 v46, v46, v48, v57
	v_div_fixup_f32 v45, v46, v45, 1.0
	v_fma_f32 v40, v56, v45, v40
	v_max_f32_e32 v40, 0xda24260, v40
	v_cmp_gt_f32_e32 vcc, s56, v40
	s_nop 1
	v_cndmask_b32_e64 v45, 0, 32, vcc
	v_ldexp_f32 v40, v40, v45
	v_log_f32_e32 v40, v40
	s_nop 0
	v_mul_f32_e32 v45, 0x3f317217, v40
	v_fma_f32 v45, v40, s57, -v45
	v_fmac_f32_e32 v45, 0x3377d1cf, v40
	v_fmac_f32_e32 v45, 0x3f317217, v40
	v_cmp_lt_f32_e64 s[0:1], |v40|, s8
	s_nop 1
	v_cndmask_b32_e64 v40, v40, v45, s[0:1]
	v_cndmask_b32_e32 v45, 0, v201, vcc
	v_sub_f32_e32 v40, v40, v45
	v_mul_f32_e32 v45, 0xbfb8aa3b, v59
	v_exp_f32_e32 v45, v45
	s_nop 0
	v_add_f32_e32 v45, 1.0, v45
	v_div_scale_f32 v46, s[0:1], v45, v45, 1.0
	v_rcp_f32_e32 v48, v46
	s_nop 0
	v_fma_f32 v49, -v46, v48, 1.0
	v_fmac_f32_e32 v48, v49, v48
	v_div_scale_f32 v49, vcc, 1.0, v45, 1.0
	v_mul_f32_e32 v56, v49, v48
	v_fma_f32 v57, -v46, v56, v49
	v_fmac_f32_e32 v56, v57, v48
	v_fma_f32 v46, -v46, v56, v49
	v_div_fmas_f32 v46, v46, v48, v56
	v_div_fixup_f32 v45, v46, v45, 1.0
	v_fmac_f32_e32 v41, v55, v45
	v_max_f32_e32 v41, 0xda24260, v41
	v_cmp_gt_f32_e32 vcc, s56, v41
	s_nop 1
	v_cndmask_b32_e64 v45, 0, 32, vcc
	v_ldexp_f32 v41, v41, v45
	v_log_f32_e32 v41, v41
	s_nop 0
	v_mul_f32_e32 v45, 0x3f317217, v41
	v_fma_f32 v45, v41, s57, -v45
	v_fmac_f32_e32 v45, 0x3377d1cf, v41
	v_fmac_f32_e32 v45, 0x3f317217, v41
	v_cmp_lt_f32_e64 s[0:1], |v41|, s8
	s_nop 1
	v_cndmask_b32_e64 v41, v41, v45, s[0:1]
	v_cndmask_b32_e32 v45, 0, v201, vcc
	v_sub_f32_e32 v41, v41, v45
	v_mul_f32_e32 v45, 0xbfb8aa3b, v60
	v_exp_f32_e32 v45, v45
	s_nop 0
	v_add_f32_e32 v45, 1.0, v45
	v_div_scale_f32 v46, s[0:1], v45, v45, 1.0
	v_rcp_f32_e32 v48, v46
	s_nop 0
	v_fma_f32 v49, -v46, v48, 1.0
	v_fmac_f32_e32 v48, v49, v48
	v_div_scale_f32 v49, vcc, 1.0, v45, 1.0
	v_mul_f32_e32 v55, v49, v48
	v_fma_f32 v56, -v46, v55, v49
	v_fmac_f32_e32 v55, v56, v48
	v_fma_f32 v46, -v46, v55, v49
	v_div_fmas_f32 v46, v46, v48, v55
	v_div_fixup_f32 v45, v46, v45, 1.0
	v_fma_f32 v34, v54, v45, v34
	v_max_f32_e32 v34, 0xda24260, v34
	v_cmp_gt_f32_e32 vcc, s56, v34
	s_nop 1
	v_cndmask_b32_e64 v45, 0, 32, vcc
	v_ldexp_f32 v34, v34, v45
	v_log_f32_e32 v34, v34
	s_nop 0
	v_mul_f32_e32 v45, 0x3f317217, v34
	v_fma_f32 v45, v34, s57, -v45
	v_fmac_f32_e32 v45, 0x3377d1cf, v34
	v_fmac_f32_e32 v45, 0x3f317217, v34
	v_cmp_lt_f32_e64 s[0:1], |v34|, s8
	s_nop 1
	v_cndmask_b32_e64 v34, v34, v45, s[0:1]
	v_cndmask_b32_e32 v45, 0, v201, vcc
	v_sub_f32_e32 v34, v34, v45
	v_div_scale_f32 v45, s[0:1], v44, v44, 1.0
	v_rcp_f32_e32 v46, v45
	s_nop 0
	v_fma_f32 v48, -v45, v46, 1.0
	v_fmac_f32_e32 v46, v48, v46
	v_div_scale_f32 v48, vcc, 1.0, v44, 1.0
	v_mul_f32_e32 v49, v48, v46
	v_fma_f32 v54, -v45, v49, v48
; __device__ __forceinline__ float sigmoidf_(float x) { return 1.0f / (1.0f + __expf(-x)); }
; __device__ __forceinline__ void hg_bcum(const Params& p, int l, const u16* Uhg, int t0, int h, float* bc, float* lbs,
;                                         float* tots) {
;     ...
;     float lf[8];
; #pragma unroll
;     for (int j = 0; j < 8; ++j) {
;       const float lbv = lbs[d0 + j];
;       const float f = lbv + (1.0f - lbv) * sigmoidf_(z[j]);
;       lf[j] = __logf(fmaxf(f, 1e-30f));
;     }
;     *(float4*)(bc + s * BCS + d0) = make_float4(lf[0], lf[1], lf[2], lf[3]);
;     *(float4*)(bc + s * BCS + d0 + 4) = make_float4(lf[4], lf[5], lf[6], lf[7]);
;   }
;   __syncthreads();
;   {
;     const int d = tid & 127, hf = tid >> 7;
;     float r[32];
;     float run = 0.f;
; #pragma unroll
;     for (int s = 0; s < 32; ++s) { run += bc[(hf * 32 + s) * BCS + d]; r[s] = run; }
;     if (hf == 0) tots[d] = run;
;     __syncthreads();
	v_fmac_f32_e32 v49, v54, v46
	v_fma_f32 v45, -v45, v49, v48
	v_div_fmas_f32 v45, v45, v46, v49
	v_div_fixup_f32 v44, v45, v44, 1.0
	v_fma_f32 v35, v53, v44, v35
	v_max_f32_e32 v35, 0xda24260, v35
	v_cmp_gt_f32_e32 vcc, s56, v35
	s_nop 1
	v_cndmask_b32_e64 v44, 0, 32, vcc
	v_ldexp_f32 v35, v35, v44
	v_log_f32_e32 v35, v35
	s_nop 0
	v_mul_f32_e32 v44, 0x3f317217, v35
	v_fma_f32 v44, v35, s57, -v44
	v_fmac_f32_e32 v44, 0x3377d1cf, v35
	v_fmac_f32_e32 v44, 0x3f317217, v35
	v_cmp_lt_f32_e64 s[0:1], |v35|, s8
	s_nop 1
	v_cndmask_b32_e64 v35, v35, v44, s[0:1]
	v_cndmask_b32_e32 v44, 0, v201, vcc
	v_sub_f32_e32 v35, v35, v44
	v_div_scale_f32 v44, s[0:1], v43, v43, 1.0
	v_rcp_f32_e32 v45, v44
	s_nop 0
	v_fma_f32 v46, -v44, v45, 1.0
	v_fmac_f32_e32 v45, v46, v45
	v_div_scale_f32 v46, vcc, 1.0, v43, 1.0
	v_mul_f32_e32 v48, v46, v45
	v_fma_f32 v49, -v44, v48, v46
	v_fmac_f32_e32 v48, v49, v45
	v_fma_f32 v44, -v44, v48, v46
	v_div_fmas_f32 v44, v44, v45, v48
	v_div_fixup_f32 v43, v44, v43, 1.0
	v_fma_f32 v36, v52, v43, v36
	v_max_f32_e32 v36, 0xda24260, v36
	v_cmp_gt_f32_e32 vcc, s56, v36
	s_nop 1
	v_cndmask_b32_e64 v43, 0, 32, vcc
	v_ldexp_f32 v36, v36, v43
	v_log_f32_e32 v36, v36
	s_nop 0
	v_mul_f32_e32 v43, 0x3f317217, v36
	v_fma_f32 v43, v36, s57, -v43
	v_fmac_f32_e32 v43, 0x3377d1cf, v36
	v_fmac_f32_e32 v43, 0x3f317217, v36
	v_cmp_lt_f32_e64 s[0:1], |v36|, s8
	s_nop 1
	v_cndmask_b32_e64 v36, v36, v43, s[0:1]
	v_cndmask_b32_e32 v43, 0, v201, vcc
	v_sub_f32_e32 v36, v36, v43
	v_div_scale_f32 v43, s[0:1], v42, v42, 1.0
	v_rcp_f32_e32 v44, v43
	s_nop 0
	v_fma_f32 v45, -v43, v44, 1.0
	v_fmac_f32_e32 v44, v45, v44
	v_div_scale_f32 v45, vcc, 1.0, v42, 1.0
	v_mul_f32_e32 v46, v45, v44
	v_fma_f32 v48, -v43, v46, v45
	v_fmac_f32_e32 v46, v48, v44
	v_fma_f32 v43, -v43, v46, v45
	v_div_fmas_f32 v43, v43, v44, v46
	v_div_fixup_f32 v42, v43, v42, 1.0
	v_fmac_f32_e32 v37, v51, v42
	v_max_f32_e32 v37, 0xda24260, v37
	v_cmp_gt_f32_e32 vcc, s56, v37
	s_nop 1
	v_cndmask_b32_e64 v42, 0, 32, vcc
	v_ldexp_f32 v37, v37, v42
	v_log_f32_e32 v37, v37
	s_nop 0
	v_mul_f32_e32 v42, 0x3f317217, v37
	v_fma_f32 v42, v37, s57, -v42
	v_fmac_f32_e32 v42, 0x3377d1cf, v37
	v_fmac_f32_e32 v42, 0x3f317217, v37
	v_cmp_lt_f32_e64 s[0:1], |v37|, s8
	s_nop 1
	v_cndmask_b32_e64 v37, v37, v42, s[0:1]
	v_cndmask_b32_e32 v42, 0, v201, vcc
	v_sub_f32_e32 v37, v37, v42
	ds_write_b128 v47, v[38:41] offset:25344
	ds_write_b128 v47, v[34:37] offset:25360
	v_lshrrev_b32_e32 v34, 2, v50
	v_and_b32_e32 v36, 0x7f, v50
	v_and_b32_e32 v34, 32, v34
	v_mul_u32_u24_e32 v34, 0x210, v34
	v_lshlrev_b32_e32 v35, 2, v36
	v_add3_u32 v34, s69, v34, v35
	s_waitcnt lgkmcnt(0)
	s_barrier
	ds_read2_b32 v[38:39], v34 offset1:132
	v_add_u32_e32 v35, 0x400, v34
	ds_read2_b32 v[40:41], v35 offset0:8 offset1:140
	v_add_u32_e32 v44, 0xc00, v34
	ds_read2_b32 v[46:47], v44 offset0:24 offset1:156
	s_waitcnt lgkmcnt(2)
	v_add_f32_e32 v37, 0, v38
	v_add_f32_e32 v38, v37, v39
	s_waitcnt lgkmcnt(1)
	v_add_f32_e32 v39, v38, v40
	v_add_f32_e32 v40, v39, v41
	v_add_u32_e32 v41, 0x800, v34
	ds_read2_b32 v[42:43], v41 offset0:16 offset1:148
	v_add_u32_e32 v45, 0x1000, v34
	ds_read2_b32 v[48:49], v45 offset0:32 offset1:164
	v_add_u32_e32 v50, 0x1400, v34
	ds_read2_b32 v[52:53], v50 offset0:40 offset1:172
	s_waitcnt lgkmcnt(2)
	v_add_f32_e32 v42, v40, v42
	v_add_f32_e32 v43, v42, v43
	v_add_f32_e32 v46, v43, v46
	v_add_f32_e32 v47, v46, v47
	s_waitcnt lgkmcnt(1)
	v_add_f32_e32 v48, v47, v48
	v_add_f32_e32 v49, v48, v49
	s_waitcnt lgkmcnt(0)
	v_add_f32_e32 v51, v49, v52
	v_add_f32_e32 v52, v51, v53
	v_add_u32_e32 v53, 0x1800, v34
	ds_read2_b32 v[56:57], v53 offset0:48 offset1:180
	v_add_u32_e32 v54, 0x1c00, v34
	ds_read2_b32 v[58:59], v54 offset0:56 offset1:188
	v_add_u32_e32 v62, 0x2400, v34
	ds_read2_b32 v[64:65], v62 offset0:72 offset1:204
	s_waitcnt lgkmcnt(2)
	v_add_f32_e32 v55, v52, v56
	v_add_f32_e32 v56, v55, v57
	s_waitcnt lgkmcnt(1)
	v_add_f32_e32 v57, v56, v58
	v_add_f32_e32 v58, v57, v59
	v_add_u32_e32 v59, 0x2000, v34
	ds_read2_b32 v[60:61], v59 offset0:64 offset1:196
	v_add_u32_e32 v63, 0x2800, v34
	ds_read2_b32 v[66:67], v63 offset0:80 offset1:212
	v_add_u32_e32 v68, 0x2c00, v34
	ds_read2_b32 v[70:71], v68 offset0:88 offset1:220
	s_waitcnt lgkmcnt(2)
	v_add_f32_e32 v60, v58, v60
	v_add_f32_e32 v61, v60, v61
	v_add_f32_e32 v64, v61, v64
	v_add_f32_e32 v65, v64, v65
	s_waitcnt lgkmcnt(1)
	v_add_f32_e32 v66, v65, v66
	v_add_f32_e32 v67, v66, v67
	s_waitcnt lgkmcnt(0)
	v_add_f32_e32 v69, v67, v70
	v_add_f32_e32 v70, v69, v71
	v_add_u32_e32 v71, 0x3000, v34
	ds_read2_b32 v[74:75], v71 offset0:96 offset1:228
	v_add_u32_e32 v72, 0x3400, v34
	ds_read2_b32 v[76:77], v72 offset0:104 offset1:236
	v_add_u32_e32 v80, 0x3c00, v34
	ds_read2_b32 v[82:83], v80 offset0:120 offset1:252
	s_waitcnt lgkmcnt(2)
	v_add_f32_e32 v73, v70, v74
	v_add_f32_e32 v74, v73, v75
	s_waitcnt lgkmcnt(1)
	v_add_f32_e32 v75, v74, v76
	v_add_f32_e32 v76, v75, v77
	v_add_u32_e32 v77, 0x3800, v34
	ds_read2_b32 v[78:79], v77 offset0:112 offset1:244
	v_lshl_add_u32 v84, v36, 2, s71
	s_waitcnt lgkmcnt(0)
	v_add_f32_e32 v78, v76, v78
	v_add_f32_e32 v79, v78, v79
	v_add_f32_e32 v81, v79, v82
	v_add_f32_e32 v82, v81, v83
	s_and_saveexec_b64 s[0:1], s[48:49]
	ds_write_b32 v84, v82
	s_or_b64 exec, exec, s[0:1]
	v_mov_b32_e32 v36, 0
	v_mov_b32_e32 v83, 0
	s_waitcnt lgkmcnt(0)
	s_barrier
; __device__ __forceinline__ void hg_bcum(const Params& p, int l, const u16* Uhg, int t0, int h, float* bc, float* lbs,
;                                         float* tots) {
;     ...
;     const float add = hf ? tots[d] : 0.f;
; #pragma unroll
;     for (int s = 0; s < 32; ++s) bc[(hf * 32 + s) * BCS + d] = r[s] + add;
;   }
;   __syncthreads();
; __device__ __forceinline__ void phase_hg_out(const Params& p, int l, char* smem) {
;     ...
;     {
;       const int d = tid & 127;
;       for (int idx = tid; idx < 64 * 128; idx += 256) {
;         const int s = idx >> 7;
;         VTs[d * 72 + s] = Uhg[(size_t)(t0 + s) * 2048 + 1024 + h * 128 + d];
;       }
;     }
	s_and_saveexec_b64 s[0:1], s[46:47]
	ds_read_b32 v83, v84
	s_or_b64 exec, exec, s[0:1]
	s_waitcnt lgkmcnt(0)
	v_add_f32_e32 v37, v37, v83
	v_add_f32_e32 v38, v38, v83
	ds_write2_b32 v34, v37, v38 offset1:132
	v_add_f32_e32 v34, v39, v83
	v_add_f32_e32 v37, v40, v83
	ds_write2_b32 v35, v34, v37 offset0:8 offset1:140
	v_add_f32_e32 v34, v42, v83
	v_add_f32_e32 v35, v43, v83
	ds_write2_b32 v41, v34, v35 offset0:16 offset1:148
	v_add_f32_e32 v34, v46, v83
	v_add_f32_e32 v35, v47, v83
	ds_write2_b32 v44, v34, v35 offset0:24 offset1:156
	v_add_f32_e32 v34, v48, v83
	v_add_f32_e32 v35, v49, v83
	ds_write2_b32 v45, v34, v35 offset0:32 offset1:164
	v_add_f32_e32 v34, v51, v83
	v_add_f32_e32 v35, v52, v83
	ds_write2_b32 v50, v34, v35 offset0:40 offset1:172
	v_add_f32_e32 v34, v55, v83
	v_add_f32_e32 v35, v56, v83
	ds_write2_b32 v53, v34, v35 offset0:48 offset1:180
	v_add_f32_e32 v34, v57, v83
	v_add_f32_e32 v35, v58, v83
	ds_write2_b32 v54, v34, v35 offset0:56 offset1:188
	v_add_f32_e32 v34, v60, v83
	v_add_f32_e32 v35, v61, v83
	ds_write2_b32 v59, v34, v35 offset0:64 offset1:196
	v_add_f32_e32 v34, v64, v83
	v_add_f32_e32 v35, v65, v83
	ds_write2_b32 v62, v34, v35 offset0:72 offset1:204
	v_add_f32_e32 v34, v66, v83
	v_add_f32_e32 v35, v67, v83
	ds_write2_b32 v63, v34, v35 offset0:80 offset1:212
	v_add_f32_e32 v34, v69, v83
	v_add_f32_e32 v35, v70, v83
	ds_write2_b32 v68, v34, v35 offset0:88 offset1:220
	v_add_f32_e32 v34, v73, v83
	v_add_f32_e32 v35, v74, v83
	ds_write2_b32 v71, v34, v35 offset0:96 offset1:228
	v_add_f32_e32 v34, v75, v83
	v_add_f32_e32 v35, v76, v83
	s_lshl_b32 s0, s20, 7
	ds_write2_b32 v72, v34, v35 offset0:104 offset1:236
	v_add_f32_e32 v34, v78, v83
	v_add_f32_e32 v35, v79, v83
	v_or_b32_e32 v38, s13, v3
	v_or_b32_e32 v40, s13, v2
	v_or_b32_e32 v42, s13, v5
	v_or_b32_e32 v44, s13, v4
	ds_write2_b32 v77, v34, v35 offset0:112 offset1:244
	v_add_f32_e32 v34, v81, v83
	v_add_f32_e32 v35, v82, v83
	s_lshl_b32 s58, s0, 1
	v_ashrrev_i32_e32 v45, 31, v44
	v_ashrrev_i32_e32 v43, 31, v42
	v_ashrrev_i32_e32 v41, 31, v40
	v_ashrrev_i32_e32 v39, 31, v38
	ds_write2_b32 v80, v34, v35 offset0:120 offset1:252
	v_lshl_add_u64 v[34:35], v[136:137], 0, s[58:59]
	v_lshlrev_b64 v[38:39], 12, v[38:39]
	v_lshlrev_b64 v[40:41], 12, v[40:41]
	v_lshlrev_b64 v[42:43], 12, v[42:43]
	v_lshlrev_b64 v[44:45], 12, v[44:45]
	v_lshl_add_u64 v[44:45], v[34:35], 0, v[44:45]
	v_lshl_add_u64 v[42:43], v[34:35], 0, v[42:43]
	v_lshl_add_u64 v[40:41], v[34:35], 0, v[40:41]
	v_lshl_add_u64 v[38:39], v[34:35], 0, v[38:39]
	global_load_ushort v98, v[44:45], off offset:2048
	s_nop 0
	global_load_ushort v99, v[42:43], off offset:2048
	s_nop 0
	global_load_ushort v100, v[40:41], off offset:2048
	s_nop 0
	global_load_ushort v101, v[38:39], off offset:2048
	v_or_b32_e32 v44, s13, v8
	v_ashrrev_i32_e32 v45, 31, v44
	v_lshlrev_b64 v[44:45], 12, v[44:45]
	v_lshl_add_u64 v[44:45], v[34:35], 0, v[44:45]
	v_mov_b32_e32 v96, 0
	v_mov_b32_e32 v97, 0
	v_mov_b32_e32 v94, 0
	v_mov_b32_e32 v95, 0
	v_or_b32_e32 v38, s13, v7
	v_or_b32_e32 v40, s13, v6
	v_or_b32_e32 v42, s13, v9
	v_ashrrev_i32_e32 v43, 31, v42
	v_ashrrev_i32_e32 v41, 31, v40
	v_ashrrev_i32_e32 v39, 31, v38
	v_lshlrev_b64 v[38:39], 12, v[38:39]
	v_lshlrev_b64 v[40:41], 12, v[40:41]
	v_lshlrev_b64 v[42:43], 12, v[42:43]
	v_lshl_add_u64 v[42:43], v[34:35], 0, v[42:43]
	v_lshl_add_u64 v[40:41], v[34:35], 0, v[40:41]
	v_lshl_add_u64 v[38:39], v[34:35], 0, v[38:39]
	global_load_ushort v102, v[44:45], off offset:2048
	s_nop 0
	global_load_ushort v103, v[42:43], off offset:2048
	s_nop 0
	global_load_ushort v104, v[40:41], off offset:2048
	s_nop 0
	global_load_ushort v105, v[38:39], off offset:2048
	v_or_b32_e32 v44, s13, v12
	v_ashrrev_i32_e32 v45, 31, v44
	v_lshlrev_b64 v[44:45], 12, v[44:45]
	v_lshl_add_u64 v[44:45], v[34:35], 0, v[44:45]
	v_or_b32_e32 v38, s13, v11
	v_or_b32_e32 v40, s13, v10
	v_or_b32_e32 v42, s13, v13
	v_ashrrev_i32_e32 v43, 31, v42
	v_ashrrev_i32_e32 v41, 31, v40
	v_ashrrev_i32_e32 v39, 31, v38
	v_lshlrev_b64 v[38:39], 12, v[38:39]
	v_lshlrev_b64 v[40:41], 12, v[40:41]
	v_lshlrev_b64 v[42:43], 12, v[42:43]
	v_lshl_add_u64 v[42:43], v[34:35], 0, v[42:43]
	v_lshl_add_u64 v[40:41], v[34:35], 0, v[40:41]
	v_lshl_add_u64 v[38:39], v[34:35], 0, v[38:39]
	global_load_ushort v106, v[44:45], off offset:2048
	s_nop 0
	global_load_ushort v107, v[42:43], off offset:2048
	s_nop 0
	global_load_ushort v108, v[40:41], off offset:2048
	s_nop 0
	global_load_ushort v109, v[38:39], off offset:2048
	v_or_b32_e32 v44, s13, v16
	v_ashrrev_i32_e32 v45, 31, v44
	v_lshlrev_b64 v[44:45], 12, v[44:45]
	v_lshl_add_u64 v[44:45], v[34:35], 0, v[44:45]
	v_or_b32_e32 v38, s13, v15
	v_or_b32_e32 v40, s13, v14
	v_or_b32_e32 v42, s13, v17
	v_ashrrev_i32_e32 v43, 31, v42
	v_ashrrev_i32_e32 v41, 31, v40
	v_ashrrev_i32_e32 v39, 31, v38
	v_lshlrev_b64 v[38:39], 12, v[38:39]
	v_lshlrev_b64 v[40:41], 12, v[40:41]
	v_lshlrev_b64 v[42:43], 12, v[42:43]
	v_lshl_add_u64 v[42:43], v[34:35], 0, v[42:43]
	v_lshl_add_u64 v[40:41], v[34:35], 0, v[40:41]
	v_lshl_add_u64 v[38:39], v[34:35], 0, v[38:39]
	global_load_ushort v110, v[44:45], off offset:2048
	s_nop 0
	global_load_ushort v111, v[42:43], off offset:2048
	s_nop 0
	global_load_ushort v112, v[40:41], off offset:2048
	s_nop 0
	global_load_ushort v113, v[38:39], off offset:2048
; __device__ __forceinline__ void phase_hg_out(const Params& p, int l, char* smem) {
;     ...
;     {
;       const int d = tid & 127;
;       for (int idx = tid; idx < 64 * 128; idx += 256) {
;         const int s = idx >> 7;
;         VTs[d * 72 + s] = Uhg[(size_t)(t0 + s) * 2048 + 1024 + h * 128 + d];
;       }
;     }
;     __syncthreads();
;     const int tt = wave * 16 + c16;
;     const bool hi = (wave >= 2);
;     bf16x8 Qt[4], Qh[4];
;     float rr8[4][8];
; #pragma unroll
;     for (int ks = 0; ks < 4; ++ks) {
;       const int d0 = ks * 32 + q * 8;
;       if (hi) load8f(bc + 31 * BCS + d0, rr8[ks]);
;       else {
; #pragma unroll
;         for (int j = 0; j < 8; ++j) rr8[ks][j] = 0.f;
;       }
;     }
; #pragma unroll
;     for (int ks = 0; ks < 4; ++ks) {
;       const int d0 = ks * 32 + q * 8;
;       const bf16x8 qraw = *(const bf16x8*)(Uhg + (size_t)(t0 + tt) * 2048 + h * 128 + d0);
	v_or_b32_e32 v38, s13, v19
	v_or_b32_e32 v40, s13, v18
	v_or_b32_e32 v42, s13, v21
	v_or_b32_e32 v44, s13, v20
	v_ashrrev_i32_e32 v45, 31, v44
	v_ashrrev_i32_e32 v43, 31, v42
	v_ashrrev_i32_e32 v41, 31, v40
	v_ashrrev_i32_e32 v39, 31, v38
	v_lshlrev_b64 v[38:39], 12, v[38:39]
	v_lshlrev_b64 v[40:41], 12, v[40:41]
	v_lshlrev_b64 v[42:43], 12, v[42:43]
	v_lshlrev_b64 v[44:45], 12, v[44:45]
	v_lshl_add_u64 v[44:45], v[34:35], 0, v[44:45]
	v_lshl_add_u64 v[42:43], v[34:35], 0, v[42:43]
	v_lshl_add_u64 v[40:41], v[34:35], 0, v[40:41]
	v_lshl_add_u64 v[38:39], v[34:35], 0, v[38:39]
	global_load_ushort v114, v[44:45], off offset:2048
	s_nop 0
	global_load_ushort v115, v[42:43], off offset:2048
	s_nop 0
	global_load_ushort v116, v[40:41], off offset:2048
	s_nop 0
	global_load_ushort v117, v[38:39], off offset:2048
	v_or_b32_e32 v38, s13, v23
	v_or_b32_e32 v40, s13, v22
	v_or_b32_e32 v42, s13, v25
	v_or_b32_e32 v44, s13, v24
	v_ashrrev_i32_e32 v45, 31, v44
	v_ashrrev_i32_e32 v43, 31, v42
	v_ashrrev_i32_e32 v41, 31, v40
	v_ashrrev_i32_e32 v39, 31, v38
	v_lshlrev_b64 v[38:39], 12, v[38:39]
	v_lshlrev_b64 v[40:41], 12, v[40:41]
	v_lshlrev_b64 v[42:43], 12, v[42:43]
	v_lshlrev_b64 v[44:45], 12, v[44:45]
	v_lshl_add_u64 v[44:45], v[34:35], 0, v[44:45]
	v_lshl_add_u64 v[42:43], v[34:35], 0, v[42:43]
	v_lshl_add_u64 v[40:41], v[34:35], 0, v[40:41]
	v_lshl_add_u64 v[38:39], v[34:35], 0, v[38:39]
	global_load_ushort v118, v[44:45], off offset:2048
	s_nop 0
	global_load_ushort v119, v[42:43], off offset:2048
	s_nop 0
	global_load_ushort v120, v[40:41], off offset:2048
	s_nop 0
	global_load_ushort v121, v[38:39], off offset:2048
	v_or_b32_e32 v38, s13, v27
	v_or_b32_e32 v40, s13, v26
	v_or_b32_e32 v42, s13, v29
	v_or_b32_e32 v44, s13, v28
	v_ashrrev_i32_e32 v45, 31, v44
	v_ashrrev_i32_e32 v43, 31, v42
	v_ashrrev_i32_e32 v41, 31, v40
	v_ashrrev_i32_e32 v39, 31, v38
	v_lshlrev_b64 v[38:39], 12, v[38:39]
	v_lshlrev_b64 v[40:41], 12, v[40:41]
	v_lshlrev_b64 v[42:43], 12, v[42:43]
	v_lshlrev_b64 v[44:45], 12, v[44:45]
	v_lshl_add_u64 v[44:45], v[34:35], 0, v[44:45]
	v_lshl_add_u64 v[42:43], v[34:35], 0, v[42:43]
	v_lshl_add_u64 v[40:41], v[34:35], 0, v[40:41]
	v_lshl_add_u64 v[38:39], v[34:35], 0, v[38:39]
	global_load_ushort v122, v[44:45], off offset:2048
	s_nop 0
	global_load_ushort v123, v[42:43], off offset:2048
	s_nop 0
	global_load_ushort v124, v[40:41], off offset:2048
	s_nop 0
	global_load_ushort v125, v[38:39], off offset:2048
	v_or_b32_e32 v38, s13, v31
	v_or_b32_e32 v40, s13, v30
	v_or_b32_e32 v42, s13, v33
	v_or_b32_e32 v44, s13, v32
	v_ashrrev_i32_e32 v45, 31, v44
	v_ashrrev_i32_e32 v43, 31, v42
	v_ashrrev_i32_e32 v41, 31, v40
	v_ashrrev_i32_e32 v39, 31, v38
	v_lshlrev_b64 v[38:39], 12, v[38:39]
	v_lshlrev_b64 v[40:41], 12, v[40:41]
	v_lshlrev_b64 v[42:43], 12, v[42:43]
	v_lshlrev_b64 v[44:45], 12, v[44:45]
	v_lshl_add_u64 v[44:45], v[34:35], 0, v[44:45]
	v_lshl_add_u64 v[42:43], v[34:35], 0, v[42:43]
	v_lshl_add_u64 v[40:41], v[34:35], 0, v[40:41]
	v_lshl_add_u64 v[34:35], v[34:35], 0, v[38:39]
	global_load_ushort v126, v[44:45], off offset:2048
	global_load_ushort v127, v[42:43], off offset:2048
	global_load_ushort v128, v[40:41], off offset:2048
	s_nop 0
	global_load_ushort v129, v[34:35], off offset:2048
	s_waitcnt lgkmcnt(0)
	s_barrier
	s_waitcnt vmcnt(0)
	ds_write_b16 v222, v98 offset:34304
	ds_write_b16 v223, v99 offset:34304
	ds_write_b16 v224, v100 offset:34304
	ds_write_b16 v225, v101 offset:34304
	ds_write_b16 v226, v102 offset:34304
	ds_write_b16 v227, v103 offset:34304
	ds_write_b16 v228, v104 offset:34304
	ds_write_b16 v229, v105 offset:34304
	ds_write_b16 v230, v106 offset:34304
	ds_write_b16 v231, v107 offset:34304
	ds_write_b16 v232, v108 offset:34304
	ds_write_b16 v233, v109 offset:34304
	ds_write_b16 v234, v110 offset:34304
	ds_write_b16 v235, v111 offset:34304
	ds_write_b16 v236, v112 offset:34304
	ds_write_b16 v237, v113 offset:34304
	ds_write_b16 v238, v114 offset:34304
	ds_write_b16 v239, v115 offset:34304
	ds_write_b16 v240, v116 offset:34304
	ds_write_b16 v241, v117 offset:34304
	ds_write_b16 v242, v118 offset:34304
	ds_write_b16 v243, v119 offset:34304
	ds_write_b16 v244, v120 offset:34304
	ds_write_b16 v245, v121 offset:34304
	ds_write_b16 v246, v122 offset:34304
	ds_write_b16 v247, v123 offset:34304
	ds_write_b16 v248, v124 offset:34304
	ds_write_b16 v249, v125 offset:34304
	ds_write_b16 v250, v126 offset:34304
	ds_write_b16 v251, v127 offset:34304
	ds_write_b16 v199, v128 offset:34304
	ds_write_b16 v200, v129 offset:34304
	v_mov_b32_e32 v37, 0
	v_mov_b32_e32 v34, 0
	v_mov_b32_e32 v35, 0
	v_or_b32_e32 v162, s13, v139
	v_ashrrev_i32_e32 v163, 31, v162
	v_readlane_b32 s0, v252, 46
	v_lshlrev_b64 v[38:39], 12, v[162:163]
	v_readlane_b32 s1, v252, 47
	v_lshl_add_u64 v[38:39], s[0:1], 0, v[38:39]
	v_lshl_add_u64 v[160:161], v[38:39], 0, s[58:59]
	v_lshl_add_u64 v[38:39], v[160:161], 0, v[0:1]
	global_load_dwordx4 v[98:101], v[38:39], off
	global_load_dwordx4 v[102:105], v[38:39], off offset:64
	global_load_dwordx4 v[106:109], v[38:39], off offset:128
	global_load_dwordx4 v[110:113], v[38:39], off offset:192
	s_waitcnt lgkmcnt(0)
	s_barrier
	s_and_saveexec_b64 s[0:1], s[50:51]
	s_cbranch_execz .LBB0_45
	ds_read_b128 v[94:97], v204 offset:16368
	ds_read_b128 v[34:37], v204 offset:16384
